# v10 + prologue silu(c) staging loop unrolled (32 loads in flight, counted waits)
# speedup vs baseline: 1.0038x; 1.0038x over previous
.LBB0_295:
	global_load_dword v100, v[0:1], off
	v_lshl_add_u64 v[0:1], v[0:1], 0, s[6:7]
	global_load_dword v101, v[0:1], off
	v_lshl_add_u64 v[0:1], v[0:1], 0, s[6:7]
	global_load_dword v102, v[0:1], off
	v_lshl_add_u64 v[0:1], v[0:1], 0, s[6:7]
	global_load_dword v103, v[0:1], off
	v_lshl_add_u64 v[0:1], v[0:1], 0, s[6:7]
	global_load_dword v104, v[0:1], off
	v_lshl_add_u64 v[0:1], v[0:1], 0, s[6:7]
	global_load_dword v105, v[0:1], off
	v_lshl_add_u64 v[0:1], v[0:1], 0, s[6:7]
	global_load_dword v106, v[0:1], off
	v_lshl_add_u64 v[0:1], v[0:1], 0, s[6:7]
	global_load_dword v107, v[0:1], off
	v_lshl_add_u64 v[0:1], v[0:1], 0, s[6:7]
	global_load_dword v108, v[0:1], off
	v_lshl_add_u64 v[0:1], v[0:1], 0, s[6:7]
	global_load_dword v109, v[0:1], off
	v_lshl_add_u64 v[0:1], v[0:1], 0, s[6:7]
	global_load_dword v110, v[0:1], off
	v_lshl_add_u64 v[0:1], v[0:1], 0, s[6:7]
	global_load_dword v111, v[0:1], off
	v_lshl_add_u64 v[0:1], v[0:1], 0, s[6:7]
	global_load_dword v112, v[0:1], off
	v_lshl_add_u64 v[0:1], v[0:1], 0, s[6:7]
	global_load_dword v113, v[0:1], off
	v_lshl_add_u64 v[0:1], v[0:1], 0, s[6:7]
	global_load_dword v114, v[0:1], off
	v_lshl_add_u64 v[0:1], v[0:1], 0, s[6:7]
	global_load_dword v115, v[0:1], off
	v_lshl_add_u64 v[0:1], v[0:1], 0, s[6:7]
	global_load_dword v116, v[0:1], off
	v_lshl_add_u64 v[0:1], v[0:1], 0, s[6:7]
	global_load_dword v117, v[0:1], off
	v_lshl_add_u64 v[0:1], v[0:1], 0, s[6:7]
	global_load_dword v118, v[0:1], off
	v_lshl_add_u64 v[0:1], v[0:1], 0, s[6:7]
	global_load_dword v119, v[0:1], off
	v_lshl_add_u64 v[0:1], v[0:1], 0, s[6:7]
	global_load_dword v120, v[0:1], off
	v_lshl_add_u64 v[0:1], v[0:1], 0, s[6:7]
	global_load_dword v121, v[0:1], off
	v_lshl_add_u64 v[0:1], v[0:1], 0, s[6:7]
	global_load_dword v122, v[0:1], off
	v_lshl_add_u64 v[0:1], v[0:1], 0, s[6:7]
	global_load_dword v123, v[0:1], off
	v_lshl_add_u64 v[0:1], v[0:1], 0, s[6:7]
	global_load_dword v124, v[0:1], off
	v_lshl_add_u64 v[0:1], v[0:1], 0, s[6:7]
	global_load_dword v125, v[0:1], off
	v_lshl_add_u64 v[0:1], v[0:1], 0, s[6:7]
	global_load_dword v126, v[0:1], off
	v_lshl_add_u64 v[0:1], v[0:1], 0, s[6:7]
	global_load_dword v127, v[0:1], off
	v_lshl_add_u64 v[0:1], v[0:1], 0, s[6:7]
	global_load_dword v128, v[0:1], off
	v_lshl_add_u64 v[0:1], v[0:1], 0, s[6:7]
	global_load_dword v129, v[0:1], off
	v_lshl_add_u64 v[0:1], v[0:1], 0, s[6:7]
	global_load_dword v130, v[0:1], off
	v_lshl_add_u64 v[0:1], v[0:1], 0, s[6:7]
	global_load_dword v131, v[0:1], off
	v_lshl_add_u64 v[0:1], v[0:1], 0, s[6:7]
	v_lshlrev_b32_e32 v136, 6, v32
	s_waitcnt vmcnt(31)
	v_mul_f32_e32 v132, 0xbfb8aa3b, v100
	v_exp_f32_e32 v132, v132
	s_nop 0
	v_add_f32_e32 v132, 1.0, v132
	v_rcp_f32_e32 v132, v132
	s_nop 0
	v_mul_f32_e32 v100, v100, v132
	ds_write_b32 v136, v100 offset:0
	s_waitcnt vmcnt(30)
	v_mul_f32_e32 v133, 0xbfb8aa3b, v101
	v_exp_f32_e32 v133, v133
	s_nop 0
	v_add_f32_e32 v133, 1.0, v133
	v_rcp_f32_e32 v133, v133
	s_nop 0
	v_mul_f32_e32 v101, v101, v133
	ds_write_b32 v136, v101 offset:32768
	s_waitcnt vmcnt(29)
	v_mul_f32_e32 v134, 0xbfb8aa3b, v102
	v_exp_f32_e32 v134, v134
	s_nop 0
	v_add_f32_e32 v134, 1.0, v134
	v_rcp_f32_e32 v134, v134
	s_nop 0
	v_mul_f32_e32 v102, v102, v134
	ds_write_b32 v136, v102 offset:4
	s_waitcnt vmcnt(28)
	v_mul_f32_e32 v135, 0xbfb8aa3b, v103
	v_exp_f32_e32 v135, v135
	s_nop 0
	v_add_f32_e32 v135, 1.0, v135
	v_rcp_f32_e32 v135, v135
	s_nop 0
	v_mul_f32_e32 v103, v103, v135
	ds_write_b32 v136, v103 offset:32772
	s_waitcnt vmcnt(27)
	v_mul_f32_e32 v132, 0xbfb8aa3b, v104
	v_exp_f32_e32 v132, v132
	s_nop 0
	v_add_f32_e32 v132, 1.0, v132
	v_rcp_f32_e32 v132, v132
	s_nop 0
	v_mul_f32_e32 v104, v104, v132
	ds_write_b32 v136, v104 offset:8
	s_waitcnt vmcnt(26)
	v_mul_f32_e32 v133, 0xbfb8aa3b, v105
	v_exp_f32_e32 v133, v133
	s_nop 0
	v_add_f32_e32 v133, 1.0, v133
	v_rcp_f32_e32 v133, v133
	s_nop 0
	v_mul_f32_e32 v105, v105, v133
	ds_write_b32 v136, v105 offset:32776
	s_waitcnt vmcnt(25)
	v_mul_f32_e32 v134, 0xbfb8aa3b, v106
	v_exp_f32_e32 v134, v134
	s_nop 0
	v_add_f32_e32 v134, 1.0, v134
	v_rcp_f32_e32 v134, v134
	s_nop 0
	v_mul_f32_e32 v106, v106, v134
	ds_write_b32 v136, v106 offset:12
	s_waitcnt vmcnt(24)
	v_mul_f32_e32 v135, 0xbfb8aa3b, v107
	v_exp_f32_e32 v135, v135
	s_nop 0
	v_add_f32_e32 v135, 1.0, v135
	v_rcp_f32_e32 v135, v135
	s_nop 0
	v_mul_f32_e32 v107, v107, v135
	ds_write_b32 v136, v107 offset:32780
	s_waitcnt vmcnt(23)
	v_mul_f32_e32 v132, 0xbfb8aa3b, v108
	v_exp_f32_e32 v132, v132
	s_nop 0
	v_add_f32_e32 v132, 1.0, v132
	v_rcp_f32_e32 v132, v132
	s_nop 0
	v_mul_f32_e32 v108, v108, v132
	ds_write_b32 v136, v108 offset:16
	s_waitcnt vmcnt(22)
	v_mul_f32_e32 v133, 0xbfb8aa3b, v109
	v_exp_f32_e32 v133, v133
	s_nop 0
	v_add_f32_e32 v133, 1.0, v133
	v_rcp_f32_e32 v133, v133
	s_nop 0
	v_mul_f32_e32 v109, v109, v133
	ds_write_b32 v136, v109 offset:32784
	s_waitcnt vmcnt(21)
	v_mul_f32_e32 v134, 0xbfb8aa3b, v110
	v_exp_f32_e32 v134, v134
	s_nop 0
	v_add_f32_e32 v134, 1.0, v134
	v_rcp_f32_e32 v134, v134
	s_nop 0
	v_mul_f32_e32 v110, v110, v134
	ds_write_b32 v136, v110 offset:20
	s_waitcnt vmcnt(20)
	v_mul_f32_e32 v135, 0xbfb8aa3b, v111
	v_exp_f32_e32 v135, v135
	s_nop 0
	v_add_f32_e32 v135, 1.0, v135
	v_rcp_f32_e32 v135, v135
	s_nop 0
	v_mul_f32_e32 v111, v111, v135
	ds_write_b32 v136, v111 offset:32788
	s_waitcnt vmcnt(19)
	v_mul_f32_e32 v132, 0xbfb8aa3b, v112
	v_exp_f32_e32 v132, v132
	s_nop 0
	v_add_f32_e32 v132, 1.0, v132
	v_rcp_f32_e32 v132, v132
	s_nop 0
	v_mul_f32_e32 v112, v112, v132
	ds_write_b32 v136, v112 offset:24
	s_waitcnt vmcnt(18)
	v_mul_f32_e32 v133, 0xbfb8aa3b, v113
	v_exp_f32_e32 v133, v133
	s_nop 0
	v_add_f32_e32 v133, 1.0, v133
	v_rcp_f32_e32 v133, v133
	s_nop 0
	v_mul_f32_e32 v113, v113, v133
	ds_write_b32 v136, v113 offset:32792
	s_waitcnt vmcnt(17)
	v_mul_f32_e32 v134, 0xbfb8aa3b, v114
	v_exp_f32_e32 v134, v134
	s_nop 0
	v_add_f32_e32 v134, 1.0, v134
	v_rcp_f32_e32 v134, v134
	s_nop 0
	v_mul_f32_e32 v114, v114, v134
	ds_write_b32 v136, v114 offset:28
	s_waitcnt vmcnt(16)
	v_mul_f32_e32 v135, 0xbfb8aa3b, v115
	v_exp_f32_e32 v135, v135
	s_nop 0
	v_add_f32_e32 v135, 1.0, v135
	v_rcp_f32_e32 v135, v135
	s_nop 0
	v_mul_f32_e32 v115, v115, v135
	ds_write_b32 v136, v115 offset:32796
	s_waitcnt vmcnt(15)
	v_mul_f32_e32 v132, 0xbfb8aa3b, v116
	v_exp_f32_e32 v132, v132
	s_nop 0
	v_add_f32_e32 v132, 1.0, v132
	v_rcp_f32_e32 v132, v132
	s_nop 0
	v_mul_f32_e32 v116, v116, v132
	ds_write_b32 v136, v116 offset:32
	s_waitcnt vmcnt(14)
	v_mul_f32_e32 v133, 0xbfb8aa3b, v117
	v_exp_f32_e32 v133, v133
	s_nop 0
	v_add_f32_e32 v133, 1.0, v133
	v_rcp_f32_e32 v133, v133
	s_nop 0
	v_mul_f32_e32 v117, v117, v133
	ds_write_b32 v136, v117 offset:32800
	s_waitcnt vmcnt(13)
	v_mul_f32_e32 v134, 0xbfb8aa3b, v118
	v_exp_f32_e32 v134, v134
	s_nop 0
	v_add_f32_e32 v134, 1.0, v134
	v_rcp_f32_e32 v134, v134
	s_nop 0
	v_mul_f32_e32 v118, v118, v134
	ds_write_b32 v136, v118 offset:36
	s_waitcnt vmcnt(12)
	v_mul_f32_e32 v135, 0xbfb8aa3b, v119
	v_exp_f32_e32 v135, v135
	s_nop 0
	v_add_f32_e32 v135, 1.0, v135
	v_rcp_f32_e32 v135, v135
	s_nop 0
	v_mul_f32_e32 v119, v119, v135
	ds_write_b32 v136, v119 offset:32804
	s_waitcnt vmcnt(11)
	v_mul_f32_e32 v132, 0xbfb8aa3b, v120
	v_exp_f32_e32 v132, v132
	s_nop 0
	v_add_f32_e32 v132, 1.0, v132
	v_rcp_f32_e32 v132, v132
	s_nop 0
	v_mul_f32_e32 v120, v120, v132
	ds_write_b32 v136, v120 offset:40
	s_waitcnt vmcnt(10)
	v_mul_f32_e32 v133, 0xbfb8aa3b, v121
	v_exp_f32_e32 v133, v133
	s_nop 0
	v_add_f32_e32 v133, 1.0, v133
	v_rcp_f32_e32 v133, v133
	s_nop 0
	v_mul_f32_e32 v121, v121, v133
	ds_write_b32 v136, v121 offset:32808
	s_waitcnt vmcnt(9)
	v_mul_f32_e32 v134, 0xbfb8aa3b, v122
	v_exp_f32_e32 v134, v134
	s_nop 0
	v_add_f32_e32 v134, 1.0, v134
	v_rcp_f32_e32 v134, v134
	s_nop 0
	v_mul_f32_e32 v122, v122, v134
	ds_write_b32 v136, v122 offset:44
	s_waitcnt vmcnt(8)
	v_mul_f32_e32 v135, 0xbfb8aa3b, v123
	v_exp_f32_e32 v135, v135
	s_nop 0
	v_add_f32_e32 v135, 1.0, v135
	v_rcp_f32_e32 v135, v135
	s_nop 0
	v_mul_f32_e32 v123, v123, v135
	ds_write_b32 v136, v123 offset:32812
	s_waitcnt vmcnt(7)
	v_mul_f32_e32 v132, 0xbfb8aa3b, v124
	v_exp_f32_e32 v132, v132
	s_nop 0
	v_add_f32_e32 v132, 1.0, v132
	v_rcp_f32_e32 v132, v132
	s_nop 0
	v_mul_f32_e32 v124, v124, v132
	ds_write_b32 v136, v124 offset:48
	s_waitcnt vmcnt(6)
	v_mul_f32_e32 v133, 0xbfb8aa3b, v125
	v_exp_f32_e32 v133, v133
	s_nop 0
	v_add_f32_e32 v133, 1.0, v133
	v_rcp_f32_e32 v133, v133
	s_nop 0
	v_mul_f32_e32 v125, v125, v133
	ds_write_b32 v136, v125 offset:32816
	s_waitcnt vmcnt(5)
	v_mul_f32_e32 v134, 0xbfb8aa3b, v126
	v_exp_f32_e32 v134, v134
	s_nop 0
	v_add_f32_e32 v134, 1.0, v134
	v_rcp_f32_e32 v134, v134
	s_nop 0
	v_mul_f32_e32 v126, v126, v134
	ds_write_b32 v136, v126 offset:52
	s_waitcnt vmcnt(4)
	v_mul_f32_e32 v135, 0xbfb8aa3b, v127
	v_exp_f32_e32 v135, v135
	s_nop 0
	v_add_f32_e32 v135, 1.0, v135
	v_rcp_f32_e32 v135, v135
	s_nop 0
	v_mul_f32_e32 v127, v127, v135
	ds_write_b32 v136, v127 offset:32820
	s_waitcnt vmcnt(3)
	v_mul_f32_e32 v132, 0xbfb8aa3b, v128
	v_exp_f32_e32 v132, v132
	s_nop 0
	v_add_f32_e32 v132, 1.0, v132
	v_rcp_f32_e32 v132, v132
	s_nop 0
	v_mul_f32_e32 v128, v128, v132
	ds_write_b32 v136, v128 offset:56
	s_waitcnt vmcnt(2)
	v_mul_f32_e32 v133, 0xbfb8aa3b, v129
	v_exp_f32_e32 v133, v133
	s_nop 0
	v_add_f32_e32 v133, 1.0, v133
	v_rcp_f32_e32 v133, v133
	s_nop 0
	v_mul_f32_e32 v129, v129, v133
	ds_write_b32 v136, v129 offset:32824
	s_waitcnt vmcnt(1)
	v_mul_f32_e32 v134, 0xbfb8aa3b, v130
	v_exp_f32_e32 v134, v134
	s_nop 0
	v_add_f32_e32 v134, 1.0, v134
	v_rcp_f32_e32 v134, v134
	s_nop 0
	v_mul_f32_e32 v130, v130, v134
	ds_write_b32 v136, v130 offset:60
	s_waitcnt vmcnt(0)
	v_mul_f32_e32 v135, 0xbfb8aa3b, v131
	v_exp_f32_e32 v135, v135
	s_nop 0
	v_add_f32_e32 v135, 1.0, v135
	v_rcp_f32_e32 v135, v135
	s_nop 0
	v_mul_f32_e32 v131, v131, v135
	ds_write_b32 v136, v131 offset:32828
